# v42 + layer 0 reads the residual rows from the model input (first norm phase and first output projections) instead of a copy made by the prologue; the prologue copies only the 768 appended rows
# speedup vs baseline: 1.0171x; 1.0115x over previous
; DI void prologue(PARAMS P, LAS unsigned char* lds, int wave, int lane) {
;     ...
;     float* X = (float*)(P.ws + WS_X);
;     for (int row = gw; row < MTOT; row += NGW) {
;         int g = 0, lr = row; if (row >= G0ROWS) { g = 1 + (row - G0ROWS) / GROWS; lr = (row - G0ROWS) % GROWS; }
;         const float* src = nullptr;
;         if (g != 0 || lr < 8192) src = P.in[0] + ((size_t)(4 * g + (lr >> 11)) * 2048 + (lr & 2047)) * D;
;         else if (lr < 8704) src = P.in[1] + (size_t)(lr - 8192) * D;
;         else if (lr < 8720) src = P.in[8] + (size_t)(lr - 8704) * D;
;         f32x4* dst = (f32x4*)(X + (size_t)row * D);
; #pragma unroll
;         for (int j = 0; j < 4; ++j) dst[lane + 64 * j] = src ? ((const f32x4*)src)[lane + 64 * j] : (f32x4){0.f, 0.f, 0.f, 0.f};
;     }
.LBB0_67:
	s_or_b64 exec, exec, s[22:23]
	s_add_i32 s2, s2, 0x2000
	s_cmp_gt_i32 s2, 0x22ff
	s_cbranch_scc1 .LBB0_86
	s_ashr_i32 s3, s2, 31
	s_load_dwordx2 s[20:21], s[16:17], 0x40
	s_load_dwordx4 s[4:7], s[16:17], 0x0
	s_lshl_b64 s[16:17], s[2:3], 12
	s_add_u32 s16, s18, s16
	v_mov_b32_e32 v3, 0
	v_lshlrev_b32_e32 v2, 4, v4
	s_addc_u32 s17, s19, s17
	v_lshl_add_u64 v[6:7], s[16:17], 0, v[2:3]
	s_mov_b64 s[16:17], 0x800
	s_ashr_i32 s11, s10, 31
	v_lshl_add_u64 v[10:11], v[6:7], 0, s[16:17]
	s_lshl_b64 s[16:17], s[10:11], 12
	s_mov_b32 s19, 0
	v_lshlrev_b32_e32 v1, 4, v4
	v_mov_b32_e32 v2, v3
	v_mov_b32_e32 v4, v3
	v_mov_b32_e32 v5, v3
	s_branch .LBB0_70
.LBB0_69:
	s_add_i32 s2, s2, s10
	s_waitcnt vmcnt(0)
	global_store_dwordx4 v[10:11], v[6:9], off offset:1024
	s_cmp_lt_i32 s2, 0x2300
	v_lshl_add_u64 v[10:11], v[10:11], 0, s[16:17]
	s_cbranch_scc0 .LBB0_86

; DI void prologue(PARAMS P, LAS unsigned char* lds, int wave, int lane) {
;     ...
;     float* X = (float*)(P.ws + WS_X);
;     for (int row = gw; row < MTOT; row += NGW) {
;         int g = 0, lr = row; if (row >= G0ROWS) { g = 1 + (row - G0ROWS) / GROWS; lr = (row - G0ROWS) % GROWS; }
;         const float* src = nullptr;
;         if (g != 0 || lr < 8192) src = P.in[0] + ((size_t)(4 * g + (lr >> 11)) * 2048 + (lr & 2047)) * D;
;         else if (lr < 8704) src = P.in[1] + (size_t)(lr - 8192) * D;
;         else if (lr < 8720) src = P.in[8] + (size_t)(lr - 8704) * D;
;         f32x4* dst = (f32x4*)(X + (size_t)row * D);
; #pragma unroll
;         for (int j = 0; j < 4; ++j) dst[lane + 64 * j] = src ? ((const f32x4*)src)[lane + 64 * j] : (f32x4){0.f, 0.f, 0.f, 0.f};
;     }
.LBB0_73:
	global_load_dwordx4 v[6:9], v1, s[22:23]
	global_load_dwordx4 v[12:15], v1, s[22:23] offset:1024
	global_load_dwordx4 v[16:19], v1, s[22:23] offset:2048
	global_load_dwordx4 v[20:23], v1, s[22:23] offset:3072
	s_waitcnt vmcnt(3)
	global_store_dwordx4 v[10:11], v[6:9], off offset:-2048
	s_waitcnt vmcnt(3)
	global_store_dwordx4 v[10:11], v[12:15], off offset:-1024
	s_waitcnt vmcnt(3)
	global_store_dwordx4 v[10:11], v[16:19], off
	s_waitcnt vmcnt(3)
	global_store_dwordx4 v[10:11], v[20:23], off offset:1024
	s_add_i32 s2, s2, s10
	s_cmp_lt_i32 s2, 0x2300
	v_lshl_add_u64 v[10:11], v[10:11], 0, s[16:17]
	s_cbranch_scc0 .LBB0_86
	s_branch .LBB0_70

; #define TIDV tid_opaque()
; #define BIDX bid_opaque()
; #define GDIM gdim_opaque()
; template <int KIND> DI void run_phase(PARAMS P, int l, int g) {
;     ...
;     else if constexpr (KIND == 7) {
;         { pg8::Gemm gm{(const bf16_t*)((unsigned char*)P.out + DS_MIXB), wl + WL_WOUT, gr, D, D}; pg8::StaticOrder S; S.init(gr, D, GDIM, (BIDX + GDIM / 2) % GDIM);
;           EpiRes E{X + (size_t)gbs * D}; pg8::gemm_phase<EpiRes, pg8::StaticOrder, true, true>(TIDV, lds, gm, S, E); }
.Lk7_mode_done:
	s_load_dwordx2 s[100:101], s[18:19], 0x0
	s_load_dwordx4 s[4:7], s[18:19], 0xe8
	s_mul_i32 s1, s96, 0x2400000
	s_mul_hi_i32 s0, s96, 0x2400000
	s_waitcnt vmcnt(0)
	v_mov_b32_e32 v0, v228
	s_waitcnt lgkmcnt(0)
	s_sub_u32 s100, s100, s6
	s_subb_u32 s101, s101, s7
	s_cmp_eq_u32 s34, 0
	s_cselect_b32 s2, 0, 0x300000
	s_sub_u32 s100, s100, s2
	s_subb_u32 s101, s101, 0
	s_cmp_lg_u32 s96, 0
	s_cbranch_scc0 .Lk7_delta_ok
	s_mov_b64 s[100:101], 0
.Lk7_delta_ok:
	s_add_u32 s1, s6, s1
	s_addc_u32 s0, s7, s0
	s_add_u32 s35, s1, 0xc480000
	s_addc_u32 s74, s0, 0
	s_cmp_eq_u32 s34, 0
	s_cselect_b64 s[38:39], -1, 0
	s_and_b64 s[0:1], s[38:39], exec
	v_mov_b32_e32 v0, v228
	s_mov_b32 s10, s92
	s_mov_b32 s1, s92
	s_mov_b32 s2, s82
	s_mov_b32 s3, s92
	s_cselect_b32 s0, 35, 32
	s_abs_i32 s10, s10
	v_cvt_f32_u32_e32 v0, s10
	s_lshr_b32 s11, s3, 31
	s_add_i32 s3, s3, s11
	s_sub_i32 s11, 0, s10
	v_rcp_iflag_f32_e32 v0, v0
	s_ashr_i32 s3, s3, 1
	s_add_i32 s3, s3, s2
	s_ashr_i32 s2, s3, 31
	v_mul_f32_e32 v0, 0x4f7ffffe, v0
	v_cvt_u32_f32_e32 v0, v0
	s_abs_i32 s3, s3
	v_writelane_b32 v254, s68, 24
	v_mov_b32_e32 v14, v228
	v_readfirstlane_b32 s12, v0
	s_mul_i32 s11, s11, s12
	s_mul_hi_u32 s11, s12, s11
	s_add_i32 s12, s12, s11
	s_mul_hi_u32 s11, s3, s12
	s_mul_i32 s11, s11, s10
	s_sub_i32 s3, s3, s11
	s_sub_i32 s11, s3, s10
	s_cmp_ge_u32 s3, s10
	s_cselect_b32 s3, s11, s3
	s_sub_i32 s11, s3, s10
	s_cmp_ge_u32 s3, s10
	s_cselect_b32 s3, s11, s3
	s_xor_b32 s3, s3, s2
	s_sub_i32 s2, s3, s2
	s_lshl_b32 s12, s0, 2
	v_writelane_b32 v254, s69, 25
	s_cmp_ge_i32 s2, s12
	v_readfirstlane_b32 s33, v14
	s_cbranch_scc1 .LBB0_227
	s_cmp_eq_u32 s98, 2
	s_cbranch_scc1 .LBB0_227
	s_ashr_i32 s11, s2, 31
	s_lshr_b32 s16, s11, 29
	s_add_i32 s36, s2, s16
	s_lshr_b32 s3, s0, 1
	s_and_b32 s16, s36, -8
	s_mov_b64 s[94:95], s[18:19]
	s_and_b32 s10, s12, 4
	s_sub_i32 s21, s2, s16
	s_add_i32 s18, s3, 1
	s_cmp_ge_i32 s21, s10
	s_mov_b64 s[16:17], -1
	s_mul_i32 s19, s18, s10
	s_cbranch_scc0 .LBB0_206
	s_sub_i32 s16, s21, s10
	s_mul_i32 s16, s16, s3
	s_add_i32 s20, s16, s19
	s_mov_b64 s[16:17], 0

;     DI void operator()(const f32x4 (&acc)[2][2][4][2], const Unit& u, int wr, int wc, int fr, int fq) const {
;         const int rowb = u.pm * 256 + wr * 64 + fr, colb = u.pn * 256 + wc * 32 + 8 * fq;
; #pragma unroll
;         for (int aq = 0; aq < 4; ++aq) {
;             const int ai = aq >> 1, m0 = (aq & 1) * 2;
;             f32x4 pre[4][2][2];
; #pragma unroll
;             for (int m = m0; m < m0 + 2; ++m)
; #pragma unroll
;                 for (int bj = 0; bj < 2; ++bj) { const f32x4* p = (const f32x4*)(x + (size_t)(rowb + ai * 128 + m * 16) * 1024 + colb + bj * 128); pre[m][bj][0] = p[0]; pre[m][bj][1] = p[1]; }
; #pragma unroll
;             for (int m = m0; m < m0 + 2; ++m)
; #pragma unroll
;                 for (int bj = 0; bj < 2; ++bj) { f32x4* p = (f32x4*)(x + (size_t)(rowb + ai * 128 + m * 16) * 1024 + colb + bj * 128); p[0] = pre[m][bj][0] + acc[ai][bj][m][0]; p[1] = pre[m][bj][1] + acc[ai][bj][m][1]; }
;         }
;     }
.LBB0_223:
	v_lshl_or_b32 v140, s65, 8, v150
	v_lshl_add_u32 v146, s50, 8, v148
	v_ashrrev_i32_e32 v141, 31, v140
	v_lshlrev_b64 v[140:141], 2, v[140:141]
	v_ashrrev_i32_e32 v147, 31, v146
	v_lshl_add_u64 v[142:143], s[38:39], 0, v[140:141]
	v_lshlrev_b64 v[144:145], 12, v[146:147]
	v_lshl_add_u64 v[184:185], v[142:143], 0, v[144:145]
	s_mov_b64 s[20:21], s[100:101]
	s_cmp_lg_u32 s34, 0
	s_cbranch_scc1 .Ler_delta
	s_cmp_lt_u32 s50, 32
	s_cbranch_scc1 .Ler_delta
	s_mov_b64 s[20:21], 0
.Ler_delta:
	v_lshl_add_u64 v[142:143], v[184:185], 0, s[20:21]
	v_mov_b32_e32 v186, v184
	v_mov_b32_e32 v187, v185
	s_mov_b64 s[20:21], 0x10000
	v_lshl_add_u64 v[146:147], v[184:185], 0, s[20:21]
	v_mov_b32_e32 v164, v142
	v_mov_b32_e32 v165, v143
	global_load_dwordx4 v[152:155], v[164:165], off offset:16
	global_load_dwordx4 v[156:159], v[164:165], off
	global_load_dwordx4 v[160:163], v[164:165], off offset:528
	global_load_dwordx4 v[164:167], v[164:165], off offset:512
	s_mov_b64 s[20:21], 0x10000
	v_lshl_add_u64 v[180:181], v[142:143], 0, s[20:21]
	global_load_dwordx4 v[168:171], v[180:181], off offset:16
	global_load_dwordx4 v[172:175], v[180:181], off
	global_load_dwordx4 v[176:179], v[180:181], off offset:528
	global_load_dwordx4 v[180:183], v[180:181], off offset:512
	s_mov_b64 s[20:21], 0x20000
	v_lshl_add_u64 v[140:141], v[184:185], 0, s[20:21]
	s_mov_b64 s[20:21], 0x30000
	v_lshl_add_u64 v[144:145], v[184:185], 0, s[20:21]
	s_mov_b64 s[20:21], 0x20000
	v_lshl_add_u64 v[208:209], v[142:143], 0, s[20:21]
	global_load_dwordx4 v[188:191], v[208:209], off offset:16
	global_load_dwordx4 v[192:195], v[208:209], off
	global_load_dwordx4 v[204:207], v[208:209], off offset:528
	global_load_dwordx4 v[208:211], v[208:209], off offset:512
	s_mov_b64 s[20:21], 0x30000
	v_lshl_add_u64 v[224:225], v[142:143], 0, s[20:21]
	global_load_dwordx4 v[212:215], v[224:225], off offset:16
	global_load_dwordx4 v[216:219], v[224:225], off
	global_load_dwordx4 v[220:223], v[224:225], off offset:528
	global_load_dwordx4 v[224:227], v[224:225], off offset:512
	s_waitcnt vmcnt(8)
	v_pk_add_f32 v[122:123], v[122:123], v[152:153]
	v_pk_add_f32 v[124:125], v[124:125], v[154:155]
	global_store_dwordx4 v[186:187], v[122:125], off offset:16
	v_pk_add_f32 v[126:127], v[126:127], v[156:157]
	v_pk_add_f32 v[128:129], v[128:129], v[158:159]
	global_store_dwordx4 v[186:187], v[126:129], off
	v_pk_add_f32 v[106:107], v[106:107], v[160:161]
	v_pk_add_f32 v[108:109], v[108:109], v[162:163]
	global_store_dwordx4 v[186:187], v[106:109], off offset:528
	v_pk_add_f32 v[110:111], v[110:111], v[164:165]
	v_pk_add_f32 v[112:113], v[112:113], v[166:167]
	global_store_dwordx4 v[186:187], v[110:113], off offset:512
	v_pk_add_f32 v[114:115], v[114:115], v[168:169]
	v_pk_add_f32 v[116:117], v[116:117], v[170:171]
	global_store_dwordx4 v[146:147], v[114:117], off offset:16
	v_pk_add_f32 v[118:119], v[118:119], v[172:173]
	v_pk_add_f32 v[120:121], v[120:121], v[174:175]
	global_store_dwordx4 v[146:147], v[118:121], off
	v_pk_add_f32 v[98:99], v[98:99], v[176:177]
	v_pk_add_f32 v[100:101], v[100:101], v[178:179]
	global_store_dwordx4 v[146:147], v[98:101], off offset:528
	v_pk_add_f32 v[102:103], v[102:103], v[180:181]
	v_pk_add_f32 v[104:105], v[104:105], v[182:183]
	global_store_dwordx4 v[146:147], v[102:105], off offset:512
	s_mov_b64 s[20:21], 0x80000
	v_lshl_add_u64 v[186:187], v[184:185], 0, s[20:21]
	s_mov_b64 s[20:21], 0x90000
	v_lshl_add_u64 v[146:147], v[184:185], 0, s[20:21]
	s_mov_b64 s[20:21], 0x80000
	v_lshl_add_u64 v[164:165], v[142:143], 0, s[20:21]
	global_load_dwordx4 v[152:155], v[164:165], off offset:16
	global_load_dwordx4 v[156:159], v[164:165], off
	global_load_dwordx4 v[160:163], v[164:165], off offset:528
	global_load_dwordx4 v[164:167], v[164:165], off offset:512
	s_mov_b64 s[20:21], 0x90000
	v_lshl_add_u64 v[180:181], v[142:143], 0, s[20:21]
	global_load_dwordx4 v[168:171], v[180:181], off offset:16
	global_load_dwordx4 v[172:175], v[180:181], off
	global_load_dwordx4 v[176:179], v[180:181], off offset:528
	global_load_dwordx4 v[180:183], v[180:181], off offset:512
	s_waitcnt vmcnt(16)
;     DI void operator()(const f32x4 (&acc)[2][2][4][2], const Unit& u, int wr, int wc, int fr, int fq) const {
;         const int rowb = u.pm * 256 + wr * 64 + fr, colb = u.pn * 256 + wc * 32 + 8 * fq;
; #pragma unroll
;         for (int aq = 0; aq < 4; ++aq) {
;             const int ai = aq >> 1, m0 = (aq & 1) * 2;
;             f32x4 pre[4][2][2];
; #pragma unroll
;             for (int m = m0; m < m0 + 2; ++m)
; #pragma unroll
;                 for (int bj = 0; bj < 2; ++bj) { const f32x4* p = (const f32x4*)(x + (size_t)(rowb + ai * 128 + m * 16) * 1024 + colb + bj * 128); pre[m][bj][0] = p[0]; pre[m][bj][1] = p[1]; }
; #pragma unroll
;             for (int m = m0; m < m0 + 2; ++m)
; #pragma unroll
;                 for (int bj = 0; bj < 2; ++bj) { f32x4* p = (f32x4*)(x + (size_t)(rowb + ai * 128 + m * 16) * 1024 + colb + bj * 128); p[0] = pre[m][bj][0] + acc[ai][bj][m][0]; p[1] = pre[m][bj][1] + acc[ai][bj][m][1]; }
;         }
;     }
	v_pk_add_f32 v[90:91], v[90:91], v[188:189]
	v_pk_add_f32 v[92:93], v[92:93], v[190:191]
	global_store_dwordx4 v[140:141], v[90:93], off offset:16
	v_pk_add_f32 v[94:95], v[94:95], v[192:193]
	v_pk_add_f32 v[96:97], v[96:97], v[194:195]
	global_store_dwordx4 v[140:141], v[94:97], off
	v_pk_add_f32 v[74:75], v[74:75], v[204:205]
	v_pk_add_f32 v[76:77], v[76:77], v[206:207]
	global_store_dwordx4 v[140:141], v[74:77], off offset:528
	v_pk_add_f32 v[78:79], v[78:79], v[208:209]
	v_pk_add_f32 v[80:81], v[80:81], v[210:211]
	global_store_dwordx4 v[140:141], v[78:81], off offset:512
	v_pk_add_f32 v[82:83], v[82:83], v[212:213]
	v_pk_add_f32 v[84:85], v[84:85], v[214:215]
	global_store_dwordx4 v[144:145], v[82:85], off offset:16
	v_pk_add_f32 v[86:87], v[86:87], v[216:217]
	v_pk_add_f32 v[88:89], v[88:89], v[218:219]
	global_store_dwordx4 v[144:145], v[86:89], off
	v_pk_add_f32 v[66:67], v[66:67], v[220:221]
	v_pk_add_f32 v[68:69], v[68:69], v[222:223]
	global_store_dwordx4 v[144:145], v[66:69], off offset:528
	v_pk_add_f32 v[70:71], v[70:71], v[224:225]
	v_pk_add_f32 v[72:73], v[72:73], v[226:227]
	global_store_dwordx4 v[144:145], v[70:73], off offset:512
	s_mov_b64 s[20:21], 0xa0000
	v_lshl_add_u64 v[140:141], v[184:185], 0, s[20:21]
	s_mov_b64 s[20:21], 0xb0000
	v_lshl_add_u64 v[144:145], v[184:185], 0, s[20:21]
	s_mov_b64 s[20:21], 0xa0000
	v_lshl_add_u64 v[208:209], v[142:143], 0, s[20:21]
	global_load_dwordx4 v[188:191], v[208:209], off offset:16
	global_load_dwordx4 v[192:195], v[208:209], off
	global_load_dwordx4 v[204:207], v[208:209], off offset:528
	global_load_dwordx4 v[208:211], v[208:209], off offset:512
	s_mov_b64 s[20:21], 0xb0000
	v_lshl_add_u64 v[224:225], v[142:143], 0, s[20:21]
	global_load_dwordx4 v[212:215], v[224:225], off offset:16
	global_load_dwordx4 v[216:219], v[224:225], off
	global_load_dwordx4 v[220:223], v[224:225], off offset:528
	global_load_dwordx4 v[224:227], v[224:225], off offset:512
	s_waitcnt vmcnt(16)
	v_pk_add_f32 v[58:59], v[58:59], v[152:153]
	v_pk_add_f32 v[60:61], v[60:61], v[154:155]
	global_store_dwordx4 v[186:187], v[58:61], off offset:16
	v_pk_add_f32 v[62:63], v[62:63], v[156:157]
	v_pk_add_f32 v[64:65], v[64:65], v[158:159]
	global_store_dwordx4 v[186:187], v[62:65], off
	v_pk_add_f32 v[42:43], v[42:43], v[160:161]
	v_pk_add_f32 v[44:45], v[44:45], v[162:163]
	global_store_dwordx4 v[186:187], v[42:45], off offset:528
	v_pk_add_f32 v[46:47], v[46:47], v[164:165]
	v_pk_add_f32 v[48:49], v[48:49], v[166:167]
	global_store_dwordx4 v[186:187], v[46:49], off offset:512
	v_pk_add_f32 v[50:51], v[50:51], v[168:169]
	v_pk_add_f32 v[52:53], v[52:53], v[170:171]
	global_store_dwordx4 v[146:147], v[50:53], off offset:16
	v_pk_add_f32 v[54:55], v[54:55], v[172:173]
	v_pk_add_f32 v[56:57], v[56:57], v[174:175]
	global_store_dwordx4 v[146:147], v[54:57], off
	v_pk_add_f32 v[34:35], v[34:35], v[176:177]
	v_pk_add_f32 v[36:37], v[36:37], v[178:179]
	global_store_dwordx4 v[146:147], v[34:37], off offset:528
	v_pk_add_f32 v[38:39], v[38:39], v[180:181]
	v_pk_add_f32 v[40:41], v[40:41], v[182:183]
	global_store_dwordx4 v[146:147], v[38:41], off offset:512
	s_waitcnt vmcnt(8)
	v_pk_add_f32 v[24:25], v[24:25], v[188:189]
	v_pk_add_f32 v[26:27], v[26:27], v[190:191]
	global_store_dwordx4 v[140:141], v[24:27], off offset:16
	v_pk_add_f32 v[28:29], v[28:29], v[192:193]
	v_pk_add_f32 v[30:31], v[30:31], v[194:195]
	global_store_dwordx4 v[140:141], v[28:31], off
	v_pk_add_f32 v[8:9], v[8:9], v[204:205]
	v_pk_add_f32 v[10:11], v[10:11], v[206:207]
	global_store_dwordx4 v[140:141], v[8:11], off offset:528
	v_pk_add_f32 v[16:17], v[16:17], v[208:209]
	v_pk_add_f32 v[18:19], v[18:19], v[210:211]
	global_store_dwordx4 v[140:141], v[16:19], off offset:512
	v_pk_add_f32 v[12:13], v[12:13], v[212:213]
	v_pk_add_f32 v[14:15], v[14:15], v[214:215]
	global_store_dwordx4 v[144:145], v[12:15], off offset:16
	v_pk_add_f32 v[20:21], v[20:21], v[216:217]
	v_pk_add_f32 v[22:23], v[22:23], v[218:219]
	global_store_dwordx4 v[144:145], v[20:23], off
	v_pk_add_f32 v[0:1], v[0:1], v[220:221]
	v_pk_add_f32 v[2:3], v[2:3], v[222:223]
	global_store_dwordx4 v[144:145], v[0:3], off offset:528
	v_pk_add_f32 v[4:5], v[4:5], v[224:225]
	v_pk_add_f32 v[6:7], v[6:7], v[226:227]
	global_store_dwordx4 v[144:145], v[4:7], off offset:512
	s_mov_b64 s[20:21], -1
	s_andn2_b64 vcc, exec, s[4:5]
	s_cbranch_vccnz .LBB0_212
	s_andn2_b64 vcc, exec, s[16:17]
	s_cbranch_vccnz .LBB0_211
	s_barrier
	s_branch .LBB0_211

; #define BIDX bid_opaque()
; #define GDIM gdim_opaque()
; DI void norm_phase(float* X, const float* gain, bf16_t* XN, const float* wsm, float* SM, int wave, int lane, const float* part = nullptr) {
;     const int gw = BIDX * 8 + wave, NGW = GDIM * 8;
;     f32x4 gv[4];
; #pragma unroll
;     for (int j = 0; j < 4; ++j) gv[j] = ((const f32x4*)gain)[lane + 64 * j];
;     if (wsm) { for (int row0 = gw * 4; row0 < MTOT; row0 += NGW * 4) norm_rows<4>(X, gv, XN, wsm, SM, row0, lane, part); }
.LBB0_940:
	s_andn2_b64 vcc, exec, s[8:9]
	s_cbranch_vccnz .LBB0_964
	s_waitcnt vmcnt(0)
	v_mov_b32_e32 v0, v228
	v_mov_b32_e32 v1, v228
	s_nop 0
	v_readfirstlane_b32 s0, v1
	s_ashr_i32 s1, s0, 6
	s_mov_b32 s0, s82
	s_lshl_b32 s2, s0, 3
	s_add_i32 s1, s2, s1
	s_load_dwordx2 s[10:11], s[18:19], 0xf0
	s_and_b32 s3, s1, 7
	s_mul_i32 s4, s96, 0x2400000
	v_and_b32_e32 v2, 63, v228
	v_lshlrev_b32_e32 v2, 4, v2
	s_lshl_b32 s3, s3, 10
	v_add_u32_e32 v2, s3, v2
	s_waitcnt lgkmcnt(0)
	s_add_u32 s10, s10, s4
	s_addc_u32 s11, s11, 0
	s_add_u32 s10, s10, 0xe860000
	s_addc_u32 s11, s11, 0
	s_add_i32 m0, s3, 0
	s_nop 0
	global_load_lds_dwordx4 v2, s[10:11]
	v_add_u32_e32 v2, 0x2000, v2
	s_add_i32 m0, s3, 8192
	s_nop 0
	global_load_lds_dwordx4 v2, s[10:11]
	v_add_u32_e32 v2, 0x2000, v2
	s_add_i32 m0, s3, 16384
	s_nop 0
	global_load_lds_dwordx4 v2, s[10:11]
	v_add_u32_e32 v2, 0x2000, v2
	s_add_i32 m0, s3, 24576
	s_nop 0
	global_load_lds_dwordx4 v2, s[10:11]
	v_add_u32_e32 v2, 0x2000, v2
	s_add_i32 m0, s3, 32768
	s_nop 0
	global_load_lds_dwordx4 v2, s[10:11]
	v_add_u32_e32 v2, 0x2000, v2
	s_add_i32 m0, s3, 40960
	s_nop 0
	global_load_lds_dwordx4 v2, s[10:11]
	v_add_u32_e32 v2, 0x2000, v2
	s_add_i32 m0, s3, 49152
	s_nop 0
	global_load_lds_dwordx4 v2, s[10:11]
	v_add_u32_e32 v2, 0x2000, v2
	s_add_i32 m0, s3, 57344
	s_nop 0
	global_load_lds_dwordx4 v2, s[10:11]
	v_add_u32_e32 v2, 0x2000, v2
	s_add_i32 m0, s3, 65536
	s_nop 0
	global_load_lds_dwordx4 v2, s[10:11]
	v_add_u32_e32 v2, 0x2000, v2
	s_add_i32 m0, s3, 73728
	s_nop 0
	global_load_lds_dwordx4 v2, s[10:11]
	v_add_u32_e32 v2, 0x2000, v2
	s_add_i32 m0, s3, 81920
	s_nop 0
	global_load_lds_dwordx4 v2, s[10:11]
	v_add_u32_e32 v2, 0x2000, v2
	s_add_i32 m0, s3, 90112
	s_nop 0
	global_load_lds_dwordx4 v2, s[10:11]
	v_add_u32_e32 v2, 0x2000, v2
	s_waitcnt vmcnt(0)
	s_barrier
	s_mov_b32 s0, s92
	s_cmpk_gt_i32 s1, 0x20bf
	s_cbranch_scc1 .LBB0_964
	s_load_dwordx2 s[2:3], s[18:19], 0x48
	s_load_dwordx2 s[10:11], s[18:19], 0xf0
	s_cmp_gt_i32 s96, 0
	s_cselect_b64 s[8:9], -1, 0
	s_lshl_b32 s4, s96, 10
	s_ashr_i32 s5, s4, 31
	s_lshl_b64 s[4:5], s[4:5], 2
	s_waitcnt lgkmcnt(0)
	s_add_u32 s2, s2, s4
	v_and_b32_e32 v18, 63, v0
	s_addc_u32 s3, s3, s5
	v_lshlrev_b32_e32 v32, 4, v18
	global_load_dwordx4 v[0:3], v32, s[2:3]
	global_load_dwordx4 v[4:7], v32, s[2:3] offset:1024
	global_load_dwordx4 v[8:11], v32, s[2:3] offset:2048
	global_load_dwordx4 v[12:15], v32, s[2:3] offset:3072
	v_lshlrev_b32_e32 v16, 2, v18
	v_mov_b32_e32 v17, v33
	v_lshl_add_u64 v[16:17], s[10:11], 0, v[16:17]
	s_mov_b64 s[2:3], 0x10c80000
	v_lshl_add_u64 v[34:35], v[16:17], 0, s[2:3]
	v_lshl_add_u64 v[36:37], s[10:11], 0, v[32:33]
	s_mov_b64 s[2:3], 0x1c67a000
	v_lshlrev_b32_e32 v16, 3, v18
	v_mov_b32_e32 v17, v33
	s_mul_i32 s12, s96, 0x2400000
	s_lshl_b32 s6, s1, 2
	s_lshl_b32 s0, s0, 5
	v_lshl_add_u64 v[38:39], v[36:37], 0, s[2:3]
	v_lshl_add_u64 v[16:17], s[10:11], 0, v[16:17]
	s_mov_b64 s[2:3], 0x8300000
	s_mul_hi_i32 s7, s96, 0x2400000
	v_lshl_add_u64 v[40:41], v[16:17], 0, s[2:3]
	s_add_u32 s2, s10, s12
	s_addc_u32 s3, s11, s7
	v_cmp_gt_u32_e64 s[4:5], 32, v18
	v_lshlrev_b32_e32 v42, 12, v18
	v_lshl_add_u64 v[44:45], s[2:3], 0, v[32:33]
	s_xor_b64 s[8:9], s[8:9], -1
	s_load_dwordx2 s[98:99], s[18:19], 0x0
	s_waitcnt lgkmcnt(0)
	v_lshl_add_u64 v[186:187], s[98:99], 0, v[32:33]
	s_branch .LBB0_944

; template <int RB> DI void norm_rows(float* X, const f32x4 (&gv)[4], bf16_t* XN, const float* wsm, float* SM, int row0, int lane, const float* part) {
;     ...
;     for (int r = 0; r < RB; ++r) {
;         const int row = row0 + r; const f32x4* xr = (const f32x4*)(X + (size_t)row * D); float ss = 0.f;
; #pragma unroll
;         for (int j = 0; j < 4; ++j) v[r][j] = xr[lane + 64 * j];
;         if (part && row >= MMAIN) {
.LBB0_944:
	s_ashr_i32 s7, s6, 31
	s_lshl_b64 s[2:3], s[6:7], 12
	v_lshl_add_u64 v[46:47], v[36:37], 0, s[2:3]
	s_cmp_lg_u32 s96, 0
	s_cbranch_scc1 .Ln1_x
	s_add_i32 s10, s6, 0xffffe000
	s_cmp_lt_u32 s10, 0x300
	s_cbranch_scc1 .Ln1_x
	s_cmp_lt_i32 s6, 0x2000
	s_cselect_b32 s10, 0, 0x300
	s_sub_i32 s10, s6, s10
	s_ashr_i32 s11, s10, 31
	s_lshl_b64 s[10:11], s[10:11], 12
	v_lshl_add_u64 v[46:47], v[186:187], 0, s[10:11]
.Ln1_x:
	global_load_dwordx4 v[28:31], v[46:47], off
	global_load_dwordx4 v[24:27], v[46:47], off offset:1024
	global_load_dwordx4 v[20:23], v[46:47], off offset:2048
	global_load_dwordx4 v[16:19], v[46:47], off offset:3072
	s_mov_b64 s[10:11], 0x1000
	v_lshl_add_u64 v[178:179], v[46:47], 0, s[10:11]
	s_mov_b64 s[10:11], 0x3000
	v_lshl_add_u64 v[180:181], v[46:47], 0, s[10:11]
	global_load_dwordx4 v[140:143], v[178:179], off
	global_load_dwordx4 v[136:139], v[178:179], off offset:1024
	global_load_dwordx4 v[132:135], v[178:179], off offset:2048
	global_load_dwordx4 v[128:131], v[178:179], off offset:3072
	global_load_dwordx4 v[156:159], v[180:181], off offset:-4096
	global_load_dwordx4 v[152:155], v[180:181], off offset:-3072
	global_load_dwordx4 v[148:151], v[180:181], off offset:-2048
	global_load_dwordx4 v[144:147], v[180:181], off offset:-1024
	global_load_dwordx4 v[172:175], v[180:181], off
	global_load_dwordx4 v[168:171], v[180:181], off offset:1024
	global_load_dwordx4 v[164:167], v[180:181], off offset:2048
	global_load_dwordx4 v[160:163], v[180:181], off offset:3072
	s_cmp_lt_i32 s6, 0x8000
	s_cselect_b64 s[2:3], -1, 0
	s_or_b64 s[2:3], s[8:9], s[2:3]
	s_and_b64 vcc, exec, s[2:3]
	s_cbranch_vccnz .LBB0_948
	s_movk_i32 s1, 0x8000
